# S5 scan pass 1 rewritten by hand (plain fma recurrences, MFMA ahead, next item prefetched) + OWN combine batching + cg sync split
# baseline (speedup 1.0000x reference)
.LBB0_135:
	s_or_b64 exec, exec, s[6:7]
	v_mul_f32_e32 v4, v4, v0
	v_mul_f32_e32 v7, 0x3fb8aa3b, v4
	s_mov_b32 s0, 0x3fb8aa3b
	v_fma_f32 v10, v4, s0, -v7
	v_rndne_f32_e32 v11, v7
	v_fmac_f32_e32 v10, 0x32a5705f, v4
	v_sub_f32_e32 v7, v7, v11
	v_add_f32_e32 v7, v7, v10
	v_lshlrev_b32_e32 v10, 6, v25
	s_movk_i32 s0, 0x800
	v_or3_b32 v23, v10, v33, s0
	v_cvt_i32_f32_e32 v22, v11
	global_load_dwordx4 v[10:13], v23, s[12:13] offset:16
	global_load_dwordx4 v[14:17], v23, s[12:13]
	global_load_dwordx4 v[18:21], v23, s[22:23] offset:16
	global_load_dwordx4 v[34:37], v23, s[22:23]
	v_exp_f32_e32 v7, v7
	s_mov_b32 s0, 0xc2ce8ed0
	v_cmp_ngt_f32_e32 vcc, s0, v4
	s_mov_b32 s0, 0x42b17218
	v_ldexp_f32 v7, v7, v22
	v_cndmask_b32_e32 v7, 0, v7, vcc
	v_cmp_nlt_f32_e32 vcc, s0, v4
	s_movk_i32 s0, 0x1f8
	v_ashrrev_i32_e32 v165, 6, v28
	v_cndmask_b32_e32 v4, v198, v7, vcc
	v_mul_f32_e32 v7, v6, v6
	v_fmamk_f32 v22, v7, 0xb94c1982, v194
	v_fmaak_f32 v22, v7, v22, 0xbe2aaa9d
	v_mul_f32_e32 v22, v7, v22
	v_fmac_f32_e32 v6, v6, v22
	v_fmamk_f32 v22, v7, 0x37d75334, v195
	v_fmaak_f32 v22, v7, v22, 0x3d2aabf7
	v_fmaak_f32 v22, v7, v22, 0xbf000004
	v_fma_f32 v7, v7, v22, 1.0
	v_and_b32_e32 v22, 1, v5
	v_cmp_eq_u32_e32 vcc, 0, v22
	v_lshlrev_b32_e32 v5, 30, v5
	s_nop 0
	v_cndmask_b32_e64 v6, -v6, v7, vcc
	v_bitop3_b32 v5, v5, v6, s35 bitop3:0x6c
	v_mul_f32_e32 v6, v9, v9
	v_fmamk_f32 v7, v6, 0xb94c1982, v194
	v_fmaak_f32 v7, v6, v7, 0xbe2aaa9d
	v_mul_f32_e32 v7, v6, v7
	v_fmac_f32_e32 v9, v9, v7
	v_fmamk_f32 v7, v6, 0x37d75334, v195
	v_fmaak_f32 v7, v6, v7, 0x3d2aabf7
	v_fmaak_f32 v7, v6, v7, 0xbf000004
	v_fma_f32 v6, v6, v7, 1.0
	v_and_b32_e32 v7, 1, v8
	v_cmp_eq_u32_e64 s[6:7], 0, v7
	v_lshlrev_b32_e32 v7, 30, v8
	v_cmp_class_f32_e64 vcc, v2, s0
	v_and_b32_e32 v7, 0x80000000, v7
	v_xor_b32_e32 v2, v3, v2
	v_cndmask_b32_e64 v6, v6, v9, s[6:7]
	v_xor_b32_e32 v2, v2, v7
	v_xor_b32_e32 v2, v2, v6
	v_cndmask_b32_e32 v2, v201, v2, vcc
	v_cndmask_b32_e32 v5, v201, v5, vcc
	v_mul_f32_e32 v154, v4, v2
	v_mul_f32_e32 v2, v1, v1
	v_fma_f32 v3, v4, v5, -1.0
	v_mul_f32_e32 v6, v1, v154
	v_fmac_f32_e32 v2, v0, v0
	v_fmac_f32_e32 v6, v0, v3
	v_div_scale_f32 v7, s[6:7], v2, v2, v6
	v_rcp_f32_e32 v8, v7
	v_mul_f32_e32 v1, v1, v3
	v_fma_f32 v0, v0, v154, -v1
	v_div_scale_f32 v1, s[6:7], v2, v2, v0
	v_fma_f32 v9, -v7, v8, 1.0
	v_fmac_f32_e32 v8, v9, v8
	v_div_scale_f32 v9, vcc, v6, v2, v6
	v_mul_f32_e32 v22, v9, v8
	v_fma_f32 v23, -v7, v22, v9
	v_rcp_f32_e32 v3, v1
	v_fmac_f32_e32 v22, v23, v8
	v_fma_f32 v7, -v7, v22, v9
	v_div_fmas_f32 v7, v7, v8, v22
	v_div_fixup_f32 v6, v7, v2, v6
	v_fma_f32 v7, -v1, v3, 1.0
	v_fmac_f32_e32 v3, v7, v3
	v_div_scale_f32 v7, vcc, v0, v2, v0
	v_mul_f32_e32 v8, v7, v3
	v_fma_f32 v9, -v1, v8, v7
	v_fmac_f32_e32 v8, v9, v3
	v_fma_f32 v1, -v1, v8, v7
	v_div_fmas_f32 v1, v1, v3, v8
	v_div_fixup_f32 v0, v1, v2, v0
	s_waitcnt vmcnt(2)
	v_mul_f32_e32 v1, v14, v0
	s_waitcnt vmcnt(0)
	v_fma_f32 v1, v34, v6, -v1
	v_mul_f32_e32 v2, v15, v0
	v_fma_f32 v2, v35, v6, -v2
	v_cvt_pk_bf16_f32 v136, v1, v2
	v_mul_f32_e32 v1, v16, v0
	v_fma_f32 v1, v36, v6, -v1
	v_mul_f32_e32 v2, v17, v0
	v_fma_f32 v2, v37, v6, -v2
	v_cvt_pk_bf16_f32 v137, v1, v2
	v_mul_f32_e32 v1, v10, v0
	v_fma_f32 v1, v18, v6, -v1
	v_mul_f32_e32 v2, v11, v0
	v_fma_f32 v2, v19, v6, -v2
	v_cvt_pk_bf16_f32 v138, v1, v2
	v_mul_f32_e32 v1, v12, v0
	v_fma_f32 v1, v20, v6, -v1
	v_mul_f32_e32 v2, v13, v0
	v_fma_f32 v2, v21, v6, -v2
	v_cvt_pk_bf16_f32 v139, v1, v2
	v_mul_f32_e32 v1, v34, v0
	v_fmac_f32_e32 v1, v14, v6
	v_mul_f32_e32 v2, v35, v0
	v_fmac_f32_e32 v2, v15, v6
	v_cvt_pk_bf16_f32 v140, v1, v2
	v_mul_f32_e32 v1, v36, v0
	v_fmac_f32_e32 v1, v16, v6
	v_mul_f32_e32 v2, v37, v0
	v_fmac_f32_e32 v2, v17, v6
	v_cvt_pk_bf16_f32 v141, v1, v2
	v_mul_f32_e32 v1, v18, v0
	v_fmac_f32_e32 v1, v10, v6
	v_mul_f32_e32 v2, v19, v0
	s_movk_i32 s0, 0x80
	v_fmac_f32_e32 v2, v11, v6
	v_cvt_pk_bf16_f32 v142, v1, v2
	v_mul_f32_e32 v1, v20, v0
	v_mul_f32_e32 v0, v21, v0
	v_cmp_gt_i32_e32 vcc, s0, v165
	v_fmac_f32_e32 v1, v12, v6
	v_fmac_f32_e32 v0, v13, v6
	v_cvt_pk_bf16_f32 v143, v1, v0
	s_and_saveexec_b64 s[6:7], vcc
	s_cbranch_execz .LBB0_138
	v_lshrrev_b32_e32 v0, 1, v24
	v_and_b32_e32 v2, 12, v0
	v_lshlrev_b32_e32 v0, 4, v24
	v_lshlrev_b32_e32 v158, 5, v26
	v_mul_f32_e32 v168, v4, v5
	v_and_b32_e32 v4, 64, v0
	v_lshl_add_u64 v[0:1], s[90:91], 0, v[158:159]
	v_lshlrev_b32_e32 v158, 1, v32
	v_lshl_add_u64 v[0:1], v[0:1], 0, v[158:159]
	s_mov_b64 s[0:1], 0x7300000
	v_lshlrev_b32_e32 v158, 3, v27
	v_lshl_add_u64 v[170:171], v[0:1], 0, s[0:1]
	v_lshl_add_u64 v[0:1], s[90:91], 0, v[158:159]
	v_lshlrev_b32_e32 v158, 3, v25
	v_mul_f32_e32 v166, v29, v30
	v_lshl_add_u64 v[0:1], v[0:1], 0, v[158:159]
	s_mov_b64 s[8:9], 0xb300000
	v_lshl_add_u64 v[172:173], v[0:1], 0, s[8:9]
	v_mul_f32_e32 v0, 0, v166
	v_mul_f32_e32 v1, 0, v152
	v_add_f32_e32 v174, v0, v1
	v_fma_f32 v175, v166, 0, -v1
	v_mul_f32_e32 v0, 0, v168
	v_mul_f32_e32 v1, 0, v154
	v_add_f32_e32 v176, v0, v1
	v_lshlrev_b32_e32 v0, 7, v165
	v_and_b32_e32 v3, 3, v24
	v_or3_b32 v0, v0, v4, v2
	v_fma_f32 v177, v168, 0, -v1
	v_mov_b32_e32 v167, v166
	v_mov_b32_e32 v153, v152
	v_mov_b32_e32 v169, v168
	v_mov_b32_e32 v155, v154
	v_mov_b32_e32 v178, v166
	v_mov_b32_e32 v179, v152
	v_mov_b32_e32 v180, v152
	v_mov_b32_e32 v181, v166
	v_mov_b32_e32 v182, v168
	v_mov_b32_e32 v183, v154
	v_mov_b32_e32 v184, v154
	v_mov_b32_e32 v185, v168
	v_lshl_or_b32 v186, v165, 1, v31
	v_or3_b32 v188, v0, v3, 48
	s_mov_b64 s[8:9], 0
	v_add_u32_e32 v12, -48, v188
	v_ashrrev_i32_e32 v13, 31, v12
	v_lshlrev_b64 v[12:13], 11, v[12:13]
	v_lshl_add_u64 v[12:13], v[170:171], 0, v[12:13]
	global_load_dwordx4 v[0:3], v[12:13], off
	v_add_u32_e32 v12, -32, v188
	v_ashrrev_i32_e32 v13, 31, v12
	v_lshlrev_b64 v[12:13], 11, v[12:13]
	v_lshl_add_u64 v[12:13], v[170:171], 0, v[12:13]
	global_load_dwordx4 v[16:19], v[12:13], off
	v_add_u32_e32 v12, -16, v188
	v_ashrrev_i32_e32 v13, 31, v12
	v_lshlrev_b64 v[12:13], 11, v[12:13]
	v_lshl_add_u64 v[12:13], v[170:171], 0, v[12:13]
	global_load_dwordx4 v[148:151], v[12:13], off
	v_add_u32_e32 v12, 0, v188
	v_ashrrev_i32_e32 v13, 31, v12
	v_lshlrev_b64 v[12:13], 11, v[12:13]
	v_lshl_add_u64 v[12:13], v[170:171], 0, v[12:13]
	global_load_dwordx4 v[144:147], v[12:13], off
	global_load_dwordx2 v[202:203], v[12:13], off
	global_load_dwordx2 v[204:205], v[12:13], off
.LBB0_137:
	v_add_u32_e32 v165, s54, v165
	v_cmp_lt_i32_e32 vcc, s36, v165
	v_add_u32_e32 v14, s84, v188
	s_or_b64 s[8:9], vcc, s[8:9]
	v_ashrrev_i32_e32 v187, 31, v186
	v_cndmask_b32_e32 v14, v14, v188, vcc
	v_mov_b32_e32 v4, 0
	v_mov_b32_e32 v5, 0
	v_mov_b32_e32 v6, 0
	v_mov_b32_e32 v7, 0
	s_waitcnt vmcnt(5)
	v_mfma_f32_32x32x16_bf16 v[20:35], v[0:3], v[128:131], 0
	v_mfma_f32_32x32x16_bf16 v[36:51], v[0:3], v[132:135], 0
	v_mfma_f32_32x32x16_bf16 v[52:67], v[0:3], v[136:139], 0
	v_mfma_f32_32x32x16_bf16 v[68:83], v[0:3], v[140:143], 0
	v_add_u32_e32 v12, -48, v14
	v_ashrrev_i32_e32 v13, 31, v12
	v_lshlrev_b64 v[12:13], 11, v[12:13]
	v_lshl_add_u64 v[12:13], v[170:171], 0, v[12:13]
	global_load_dwordx4 v[0:3], v[12:13], off
	s_waitcnt vmcnt(5)
	v_mfma_f32_32x32x16_bf16 v[84:99], v[16:19], v[128:131], 0
	v_mfma_f32_32x32x16_bf16 v[100:115], v[16:19], v[132:135], 0
	v_mfma_f32_32x32x16_bf16 v[216:231], v[16:19], v[136:139], 0
	v_mfma_f32_32x32x16_bf16 v[232:247], v[16:19], v[140:143], 0
	v_add_u32_e32 v12, -32, v14
	v_ashrrev_i32_e32 v13, 31, v12
	v_lshlrev_b64 v[12:13], 11, v[12:13]
	v_lshl_add_u64 v[12:13], v[170:171], 0, v[12:13]
	global_load_dwordx4 v[16:19], v[12:13], off
	s_nop 7
	v_fma_f32 v8, v166, v4, v20
	v_fma_f32 v9, v166, v5, v36
	v_fma_f32 v10, v168, v6, v52
	v_fma_f32 v11, v168, v7, v68
	v_fma_f32 v8, -v152, v5, v8
	v_fma_f32 v9, v152, v4, v9
	v_fma_f32 v10, -v154, v7, v10
	v_fma_f32 v11, v154, v6, v11
	v_fma_f32 v4, v166, v8, v21
	v_fma_f32 v5, v166, v9, v37
	v_fma_f32 v6, v168, v10, v53
	v_fma_f32 v7, v168, v11, v69
	v_fma_f32 v4, -v152, v9, v4
	v_fma_f32 v5, v152, v8, v5
	v_fma_f32 v6, -v154, v11, v6
	v_fma_f32 v7, v154, v10, v7
	v_fma_f32 v8, v166, v4, v22
	v_fma_f32 v9, v166, v5, v38
	v_fma_f32 v10, v168, v6, v54
	v_fma_f32 v11, v168, v7, v70
	v_fma_f32 v8, -v152, v5, v8
	v_fma_f32 v9, v152, v4, v9
	v_fma_f32 v10, -v154, v7, v10
	v_fma_f32 v11, v154, v6, v11
	v_fma_f32 v4, v166, v8, v23
	v_fma_f32 v5, v166, v9, v39
	v_fma_f32 v6, v168, v10, v55
	v_fma_f32 v7, v168, v11, v71
	v_fma_f32 v4, -v152, v9, v4
	v_fma_f32 v5, v152, v8, v5
	v_fma_f32 v6, -v154, v11, v6
	v_fma_f32 v7, v154, v10, v7
	v_fma_f32 v8, v166, v4, v24
	v_fma_f32 v9, v166, v5, v40
	v_fma_f32 v10, v168, v6, v56
	v_fma_f32 v11, v168, v7, v72
	v_fma_f32 v8, -v152, v5, v8
	v_fma_f32 v9, v152, v4, v9
	v_fma_f32 v10, -v154, v7, v10
	v_fma_f32 v11, v154, v6, v11
	v_fma_f32 v4, v166, v8, v25
	v_fma_f32 v5, v166, v9, v41
	v_fma_f32 v6, v168, v10, v57
	v_fma_f32 v7, v168, v11, v73
	v_fma_f32 v4, -v152, v9, v4
	v_fma_f32 v5, v152, v8, v5
	v_fma_f32 v6, -v154, v11, v6
	v_fma_f32 v7, v154, v10, v7
	v_fma_f32 v8, v166, v4, v26
	v_fma_f32 v9, v166, v5, v42
	v_fma_f32 v10, v168, v6, v58
	v_fma_f32 v11, v168, v7, v74
	v_fma_f32 v8, -v152, v5, v8
	v_fma_f32 v9, v152, v4, v9
	v_fma_f32 v10, -v154, v7, v10
	v_fma_f32 v11, v154, v6, v11
	v_fma_f32 v4, v166, v8, v27
	v_fma_f32 v5, v166, v9, v43
	v_fma_f32 v6, v168, v10, v59
	v_fma_f32 v7, v168, v11, v75
	v_fma_f32 v4, -v152, v9, v4
	v_fma_f32 v5, v152, v8, v5
	v_fma_f32 v6, -v154, v11, v6
	v_fma_f32 v7, v154, v10, v7
	v_fma_f32 v8, v166, v4, v28
	v_fma_f32 v9, v166, v5, v44
	v_fma_f32 v10, v168, v6, v60
	v_fma_f32 v11, v168, v7, v76
	v_fma_f32 v8, -v152, v5, v8
	v_fma_f32 v9, v152, v4, v9
	v_fma_f32 v10, -v154, v7, v10
	v_fma_f32 v11, v154, v6, v11
	v_fma_f32 v4, v166, v8, v29
	v_fma_f32 v5, v166, v9, v45
	v_fma_f32 v6, v168, v10, v61
	v_fma_f32 v7, v168, v11, v77
	v_fma_f32 v4, -v152, v9, v4
	v_fma_f32 v5, v152, v8, v5
	v_fma_f32 v6, -v154, v11, v6
	v_fma_f32 v7, v154, v10, v7
	v_fma_f32 v8, v166, v4, v30
	v_fma_f32 v9, v166, v5, v46
	v_fma_f32 v10, v168, v6, v62
	v_fma_f32 v11, v168, v7, v78
	v_fma_f32 v8, -v152, v5, v8
	v_fma_f32 v9, v152, v4, v9
	v_fma_f32 v10, -v154, v7, v10
	v_fma_f32 v11, v154, v6, v11
	v_fma_f32 v4, v166, v8, v31
	v_fma_f32 v5, v166, v9, v47
	v_fma_f32 v6, v168, v10, v63
	v_fma_f32 v7, v168, v11, v79
	v_fma_f32 v4, -v152, v9, v4
	v_fma_f32 v5, v152, v8, v5
	v_fma_f32 v6, -v154, v11, v6
	v_fma_f32 v7, v154, v10, v7
	v_fma_f32 v8, v166, v4, v32
	v_fma_f32 v9, v166, v5, v48
	v_fma_f32 v10, v168, v6, v64
	v_fma_f32 v11, v168, v7, v80
	v_fma_f32 v8, -v152, v5, v8
	v_fma_f32 v9, v152, v4, v9
	v_fma_f32 v10, -v154, v7, v10
	v_fma_f32 v11, v154, v6, v11
	v_fma_f32 v4, v166, v8, v33
	v_fma_f32 v5, v166, v9, v49
	v_fma_f32 v6, v168, v10, v65
	v_fma_f32 v7, v168, v11, v81
	v_fma_f32 v4, -v152, v9, v4
	v_fma_f32 v5, v152, v8, v5
	v_fma_f32 v6, -v154, v11, v6
	v_fma_f32 v7, v154, v10, v7
	v_fma_f32 v8, v166, v4, v34
	v_fma_f32 v9, v166, v5, v50
	v_fma_f32 v10, v168, v6, v66
	v_fma_f32 v11, v168, v7, v82
	v_fma_f32 v8, -v152, v5, v8
	v_fma_f32 v9, v152, v4, v9
	v_fma_f32 v10, -v154, v7, v10
	v_fma_f32 v11, v154, v6, v11
	v_fma_f32 v4, v166, v8, v35
	v_fma_f32 v5, v166, v9, v51
	v_fma_f32 v6, v168, v10, v67
	v_fma_f32 v7, v168, v11, v83
	v_fma_f32 v4, -v152, v9, v4
	v_fma_f32 v5, v152, v8, v5
	v_fma_f32 v6, -v154, v11, v6
	v_fma_f32 v7, v154, v10, v7
	s_waitcnt vmcnt(5)
	v_mfma_f32_32x32x16_bf16 v[20:35], v[148:151], v[128:131], 0
	v_mfma_f32_32x32x16_bf16 v[36:51], v[148:151], v[132:135], 0
	v_mfma_f32_32x32x16_bf16 v[52:67], v[148:151], v[136:139], 0
	v_mfma_f32_32x32x16_bf16 v[68:83], v[148:151], v[140:143], 0
	v_add_u32_e32 v12, -16, v14
	v_ashrrev_i32_e32 v13, 31, v12
	v_lshlrev_b64 v[12:13], 11, v[12:13]
	v_lshl_add_u64 v[12:13], v[170:171], 0, v[12:13]
	global_load_dwordx4 v[148:151], v[12:13], off
	v_fma_f32 v8, v166, v4, v84
	v_fma_f32 v9, v166, v5, v100
	v_fma_f32 v10, v168, v6, v216
	v_fma_f32 v11, v168, v7, v232
	v_fma_f32 v8, -v152, v5, v8
	v_fma_f32 v9, v152, v4, v9
	v_fma_f32 v10, -v154, v7, v10
	v_fma_f32 v11, v154, v6, v11
	v_fma_f32 v4, v166, v8, v85
	v_fma_f32 v5, v166, v9, v101
	v_fma_f32 v6, v168, v10, v217
	v_fma_f32 v7, v168, v11, v233
	v_fma_f32 v4, -v152, v9, v4
	v_fma_f32 v5, v152, v8, v5
	v_fma_f32 v6, -v154, v11, v6
	v_fma_f32 v7, v154, v10, v7
	v_fma_f32 v8, v166, v4, v86
	v_fma_f32 v9, v166, v5, v102
	v_fma_f32 v10, v168, v6, v218
	v_fma_f32 v11, v168, v7, v234
	v_fma_f32 v8, -v152, v5, v8
	v_fma_f32 v9, v152, v4, v9
	v_fma_f32 v10, -v154, v7, v10
	v_fma_f32 v11, v154, v6, v11
	v_fma_f32 v4, v166, v8, v87
	v_fma_f32 v5, v166, v9, v103
	v_fma_f32 v6, v168, v10, v219
	v_fma_f32 v7, v168, v11, v235
	v_fma_f32 v4, -v152, v9, v4
	v_fma_f32 v5, v152, v8, v5
	v_fma_f32 v6, -v154, v11, v6
	v_fma_f32 v7, v154, v10, v7
	v_fma_f32 v8, v166, v4, v88
	v_fma_f32 v9, v166, v5, v104
	v_fma_f32 v10, v168, v6, v220
	v_fma_f32 v11, v168, v7, v236
	v_fma_f32 v8, -v152, v5, v8
	v_fma_f32 v9, v152, v4, v9
	v_fma_f32 v10, -v154, v7, v10
	v_fma_f32 v11, v154, v6, v11
	v_fma_f32 v4, v166, v8, v89
	v_fma_f32 v5, v166, v9, v105
	v_fma_f32 v6, v168, v10, v221
	v_fma_f32 v7, v168, v11, v237
	v_fma_f32 v4, -v152, v9, v4
	v_fma_f32 v5, v152, v8, v5
	v_fma_f32 v6, -v154, v11, v6
	v_fma_f32 v7, v154, v10, v7
	v_fma_f32 v8, v166, v4, v90
	v_fma_f32 v9, v166, v5, v106
	v_fma_f32 v10, v168, v6, v222
	v_fma_f32 v11, v168, v7, v238
	v_fma_f32 v8, -v152, v5, v8
	v_fma_f32 v9, v152, v4, v9
	v_fma_f32 v10, -v154, v7, v10
	v_fma_f32 v11, v154, v6, v11
	v_fma_f32 v4, v166, v8, v91
	v_fma_f32 v5, v166, v9, v107
	v_fma_f32 v6, v168, v10, v223
	v_fma_f32 v7, v168, v11, v239
	v_fma_f32 v4, -v152, v9, v4
	v_fma_f32 v5, v152, v8, v5
	v_fma_f32 v6, -v154, v11, v6
	v_fma_f32 v7, v154, v10, v7
	v_fma_f32 v8, v166, v4, v92
	v_fma_f32 v9, v166, v5, v108
	v_fma_f32 v10, v168, v6, v224
	v_fma_f32 v11, v168, v7, v240
	v_fma_f32 v8, -v152, v5, v8
	v_fma_f32 v9, v152, v4, v9
	v_fma_f32 v10, -v154, v7, v10
	v_fma_f32 v11, v154, v6, v11
	v_fma_f32 v4, v166, v8, v93
	v_fma_f32 v5, v166, v9, v109
	v_fma_f32 v6, v168, v10, v225
	v_fma_f32 v7, v168, v11, v241
	v_fma_f32 v4, -v152, v9, v4
	v_fma_f32 v5, v152, v8, v5
	v_fma_f32 v6, -v154, v11, v6
	v_fma_f32 v7, v154, v10, v7
	v_fma_f32 v8, v166, v4, v94
	v_fma_f32 v9, v166, v5, v110
	v_fma_f32 v10, v168, v6, v226
	v_fma_f32 v11, v168, v7, v242
	v_fma_f32 v8, -v152, v5, v8
	v_fma_f32 v9, v152, v4, v9
	v_fma_f32 v10, -v154, v7, v10
	v_fma_f32 v11, v154, v6, v11
	v_fma_f32 v4, v166, v8, v95
	v_fma_f32 v5, v166, v9, v111
	v_fma_f32 v6, v168, v10, v227
	v_fma_f32 v7, v168, v11, v243
	v_fma_f32 v4, -v152, v9, v4
	v_fma_f32 v5, v152, v8, v5
	v_fma_f32 v6, -v154, v11, v6
	v_fma_f32 v7, v154, v10, v7
	v_fma_f32 v8, v166, v4, v96
	v_fma_f32 v9, v166, v5, v112
	v_fma_f32 v10, v168, v6, v228
	v_fma_f32 v11, v168, v7, v244
	v_fma_f32 v8, -v152, v5, v8
	v_fma_f32 v9, v152, v4, v9
	v_fma_f32 v10, -v154, v7, v10
	v_fma_f32 v11, v154, v6, v11
	v_fma_f32 v4, v166, v8, v97
	v_fma_f32 v5, v166, v9, v113
	v_fma_f32 v6, v168, v10, v229
	v_fma_f32 v7, v168, v11, v245
	v_fma_f32 v4, -v152, v9, v4
	v_fma_f32 v5, v152, v8, v5
	v_fma_f32 v6, -v154, v11, v6
	v_fma_f32 v7, v154, v10, v7
	v_fma_f32 v8, v166, v4, v98
	v_fma_f32 v9, v166, v5, v114
	v_fma_f32 v10, v168, v6, v230
	v_fma_f32 v11, v168, v7, v246
	v_fma_f32 v8, -v152, v5, v8
	v_fma_f32 v9, v152, v4, v9
	v_fma_f32 v10, -v154, v7, v10
	v_fma_f32 v11, v154, v6, v11
	v_fma_f32 v4, v166, v8, v99
	v_fma_f32 v5, v166, v9, v115
	v_fma_f32 v6, v168, v10, v231
	v_fma_f32 v7, v168, v11, v247
	v_fma_f32 v4, -v152, v9, v4
	v_fma_f32 v5, v152, v8, v5
	v_fma_f32 v6, -v154, v11, v6
	v_fma_f32 v7, v154, v10, v7
	s_waitcnt vmcnt(5)
	v_mfma_f32_32x32x16_bf16 v[84:99], v[144:147], v[128:131], 0
	v_mfma_f32_32x32x16_bf16 v[100:115], v[144:147], v[132:135], 0
	v_mfma_f32_32x32x16_bf16 v[216:231], v[144:147], v[136:139], 0
	v_mfma_f32_32x32x16_bf16 v[232:247], v[144:147], v[140:143], 0
	v_add_u32_e32 v12, 0, v14
	v_ashrrev_i32_e32 v13, 31, v12
	v_lshlrev_b64 v[12:13], 11, v[12:13]
	v_lshl_add_u64 v[12:13], v[170:171], 0, v[12:13]
	global_load_dwordx4 v[144:147], v[12:13], off
	v_fma_f32 v8, v166, v4, v20
	v_fma_f32 v9, v166, v5, v36
	v_fma_f32 v10, v168, v6, v52
	v_fma_f32 v11, v168, v7, v68
	v_fma_f32 v8, -v152, v5, v8
	v_fma_f32 v9, v152, v4, v9
	v_fma_f32 v10, -v154, v7, v10
	v_fma_f32 v11, v154, v6, v11
	v_fma_f32 v4, v166, v8, v21
	v_fma_f32 v5, v166, v9, v37
	v_fma_f32 v6, v168, v10, v53
	v_fma_f32 v7, v168, v11, v69
	v_fma_f32 v4, -v152, v9, v4
	v_fma_f32 v5, v152, v8, v5
	v_fma_f32 v6, -v154, v11, v6
	v_fma_f32 v7, v154, v10, v7
	v_fma_f32 v8, v166, v4, v22
	v_fma_f32 v9, v166, v5, v38
	v_fma_f32 v10, v168, v6, v54
	v_fma_f32 v11, v168, v7, v70
	v_fma_f32 v8, -v152, v5, v8
	v_fma_f32 v9, v152, v4, v9
	v_fma_f32 v10, -v154, v7, v10
	v_fma_f32 v11, v154, v6, v11
	v_fma_f32 v4, v166, v8, v23
	v_fma_f32 v5, v166, v9, v39
	v_fma_f32 v6, v168, v10, v55
	v_fma_f32 v7, v168, v11, v71
	v_fma_f32 v4, -v152, v9, v4
	v_fma_f32 v5, v152, v8, v5
	v_fma_f32 v6, -v154, v11, v6
	v_fma_f32 v7, v154, v10, v7
	v_fma_f32 v8, v166, v4, v24
	v_fma_f32 v9, v166, v5, v40
	v_fma_f32 v10, v168, v6, v56
	v_fma_f32 v11, v168, v7, v72
	v_fma_f32 v8, -v152, v5, v8
	v_fma_f32 v9, v152, v4, v9
	v_fma_f32 v10, -v154, v7, v10
	v_fma_f32 v11, v154, v6, v11
	v_fma_f32 v4, v166, v8, v25
	v_fma_f32 v5, v166, v9, v41
	v_fma_f32 v6, v168, v10, v57
	v_fma_f32 v7, v168, v11, v73
	v_fma_f32 v4, -v152, v9, v4
	v_fma_f32 v5, v152, v8, v5
	v_fma_f32 v6, -v154, v11, v6
	v_fma_f32 v7, v154, v10, v7
	v_fma_f32 v8, v166, v4, v26
	v_fma_f32 v9, v166, v5, v42
	v_fma_f32 v10, v168, v6, v58
	v_fma_f32 v11, v168, v7, v74
	v_fma_f32 v8, -v152, v5, v8
	v_fma_f32 v9, v152, v4, v9
	v_fma_f32 v10, -v154, v7, v10
	v_fma_f32 v11, v154, v6, v11
	v_fma_f32 v4, v166, v8, v27
	v_fma_f32 v5, v166, v9, v43
	v_fma_f32 v6, v168, v10, v59
	v_fma_f32 v7, v168, v11, v75
	v_fma_f32 v4, -v152, v9, v4
	v_fma_f32 v5, v152, v8, v5
	v_fma_f32 v6, -v154, v11, v6
	v_fma_f32 v7, v154, v10, v7
	v_fma_f32 v8, v166, v4, v28
	v_fma_f32 v9, v166, v5, v44
	v_fma_f32 v10, v168, v6, v60
	v_fma_f32 v11, v168, v7, v76
	v_fma_f32 v8, -v152, v5, v8
	v_fma_f32 v9, v152, v4, v9
	v_fma_f32 v10, -v154, v7, v10
	v_fma_f32 v11, v154, v6, v11
	v_fma_f32 v4, v166, v8, v29
	v_fma_f32 v5, v166, v9, v45
	v_fma_f32 v6, v168, v10, v61
	v_fma_f32 v7, v168, v11, v77
	v_fma_f32 v4, -v152, v9, v4
	v_fma_f32 v5, v152, v8, v5
	v_fma_f32 v6, -v154, v11, v6
	v_fma_f32 v7, v154, v10, v7
	v_fma_f32 v8, v166, v4, v30
	v_fma_f32 v9, v166, v5, v46
	v_fma_f32 v10, v168, v6, v62
	v_fma_f32 v11, v168, v7, v78
	v_fma_f32 v8, -v152, v5, v8
	v_fma_f32 v9, v152, v4, v9
	v_fma_f32 v10, -v154, v7, v10
	v_fma_f32 v11, v154, v6, v11
	v_fma_f32 v4, v166, v8, v31
	v_fma_f32 v5, v166, v9, v47
	v_fma_f32 v6, v168, v10, v63
	v_fma_f32 v7, v168, v11, v79
	v_fma_f32 v4, -v152, v9, v4
	v_fma_f32 v5, v152, v8, v5
	v_fma_f32 v6, -v154, v11, v6
	v_fma_f32 v7, v154, v10, v7
	v_fma_f32 v8, v166, v4, v32
	v_fma_f32 v9, v166, v5, v48
	v_fma_f32 v10, v168, v6, v64
	v_fma_f32 v11, v168, v7, v80
	v_fma_f32 v8, -v152, v5, v8
	v_fma_f32 v9, v152, v4, v9
	v_fma_f32 v10, -v154, v7, v10
	v_fma_f32 v11, v154, v6, v11
	v_fma_f32 v4, v166, v8, v33
	v_fma_f32 v5, v166, v9, v49
	v_fma_f32 v6, v168, v10, v65
	v_fma_f32 v7, v168, v11, v81
	v_fma_f32 v4, -v152, v9, v4
	v_fma_f32 v5, v152, v8, v5
	v_fma_f32 v6, -v154, v11, v6
	v_fma_f32 v7, v154, v10, v7
	v_fma_f32 v8, v166, v4, v34
	v_fma_f32 v9, v166, v5, v50
	v_fma_f32 v10, v168, v6, v66
	v_fma_f32 v11, v168, v7, v82
	v_fma_f32 v8, -v152, v5, v8
	v_fma_f32 v9, v152, v4, v9
	v_fma_f32 v10, -v154, v7, v10
	v_fma_f32 v11, v154, v6, v11
	v_fma_f32 v4, v166, v8, v35
	v_fma_f32 v5, v166, v9, v51
	v_fma_f32 v6, v168, v10, v67
	v_fma_f32 v7, v168, v11, v83
	v_fma_f32 v4, -v152, v9, v4
	v_fma_f32 v5, v152, v8, v5
	v_fma_f32 v6, -v154, v11, v6
	v_fma_f32 v7, v154, v10, v7
	v_lshlrev_b64 v[12:13], 15, v[186:187]
	v_lshl_add_u64 v[12:13], v[172:173], 0, v[12:13]
	v_add_u32_e32 v186, s5, v186
	v_mov_b32_e32 v188, v14
	v_fma_f32 v8, v166, v4, v84
	v_fma_f32 v9, v166, v5, v100
	v_fma_f32 v10, v168, v6, v216
	v_fma_f32 v11, v168, v7, v232
	v_fma_f32 v8, -v152, v5, v8
	v_fma_f32 v9, v152, v4, v9
	v_fma_f32 v10, -v154, v7, v10
	v_fma_f32 v11, v154, v6, v11
	v_fma_f32 v4, v166, v8, v85
	v_fma_f32 v5, v166, v9, v101
	v_fma_f32 v6, v168, v10, v217
	v_fma_f32 v7, v168, v11, v233
	v_fma_f32 v4, -v152, v9, v4
	v_fma_f32 v5, v152, v8, v5
	v_fma_f32 v6, -v154, v11, v6
	v_fma_f32 v7, v154, v10, v7
	v_fma_f32 v8, v166, v4, v86
	v_fma_f32 v9, v166, v5, v102
	v_fma_f32 v10, v168, v6, v218
	v_fma_f32 v11, v168, v7, v234
	v_fma_f32 v8, -v152, v5, v8
	v_fma_f32 v9, v152, v4, v9
	v_fma_f32 v10, -v154, v7, v10
	v_fma_f32 v11, v154, v6, v11
	v_fma_f32 v4, v166, v8, v87
	v_fma_f32 v5, v166, v9, v103
	v_fma_f32 v6, v168, v10, v219
	v_fma_f32 v7, v168, v11, v235
	v_fma_f32 v4, -v152, v9, v4
	v_fma_f32 v5, v152, v8, v5
	v_fma_f32 v6, -v154, v11, v6
	v_fma_f32 v7, v154, v10, v7
	v_fma_f32 v8, v166, v4, v88
	v_fma_f32 v9, v166, v5, v104
	v_fma_f32 v10, v168, v6, v220
	v_fma_f32 v11, v168, v7, v236
	v_fma_f32 v8, -v152, v5, v8
	v_fma_f32 v9, v152, v4, v9
	v_fma_f32 v10, -v154, v7, v10
	v_fma_f32 v11, v154, v6, v11
	v_fma_f32 v4, v166, v8, v89
	v_fma_f32 v5, v166, v9, v105
	v_fma_f32 v6, v168, v10, v221
	v_fma_f32 v7, v168, v11, v237
	v_fma_f32 v4, -v152, v9, v4
	v_fma_f32 v5, v152, v8, v5
	v_fma_f32 v6, -v154, v11, v6
	v_fma_f32 v7, v154, v10, v7
	v_fma_f32 v8, v166, v4, v90
	v_fma_f32 v9, v166, v5, v106
	v_fma_f32 v10, v168, v6, v222
	v_fma_f32 v11, v168, v7, v238
	v_fma_f32 v8, -v152, v5, v8
	v_fma_f32 v9, v152, v4, v9
	v_fma_f32 v10, -v154, v7, v10
	v_fma_f32 v11, v154, v6, v11
	v_fma_f32 v4, v166, v8, v91
	v_fma_f32 v5, v166, v9, v107
	v_fma_f32 v6, v168, v10, v223
	v_fma_f32 v7, v168, v11, v239
	v_fma_f32 v4, -v152, v9, v4
	v_fma_f32 v5, v152, v8, v5
	v_fma_f32 v6, -v154, v11, v6
	v_fma_f32 v7, v154, v10, v7
	v_fma_f32 v8, v166, v4, v92
	v_fma_f32 v9, v166, v5, v108
	v_fma_f32 v10, v168, v6, v224
	v_fma_f32 v11, v168, v7, v240
	v_fma_f32 v8, -v152, v5, v8
	v_fma_f32 v9, v152, v4, v9
	v_fma_f32 v10, -v154, v7, v10
	v_fma_f32 v11, v154, v6, v11
	v_fma_f32 v4, v166, v8, v93
	v_fma_f32 v5, v166, v9, v109
	v_fma_f32 v6, v168, v10, v225
	v_fma_f32 v7, v168, v11, v241
	v_fma_f32 v4, -v152, v9, v4
	v_fma_f32 v5, v152, v8, v5
	v_fma_f32 v6, -v154, v11, v6
	v_fma_f32 v7, v154, v10, v7
	v_fma_f32 v8, v166, v4, v94
	v_fma_f32 v9, v166, v5, v110
	v_fma_f32 v10, v168, v6, v226
	v_fma_f32 v11, v168, v7, v242
	v_fma_f32 v8, -v152, v5, v8
	v_fma_f32 v9, v152, v4, v9
	v_fma_f32 v10, -v154, v7, v10
	v_fma_f32 v11, v154, v6, v11
	v_fma_f32 v4, v166, v8, v95
	v_fma_f32 v5, v166, v9, v111
	v_fma_f32 v6, v168, v10, v227
	v_fma_f32 v7, v168, v11, v243
	v_fma_f32 v4, -v152, v9, v4
	v_fma_f32 v5, v152, v8, v5
	v_fma_f32 v6, -v154, v11, v6
	v_fma_f32 v7, v154, v10, v7
	v_fma_f32 v8, v166, v4, v96
	v_fma_f32 v9, v166, v5, v112
	v_fma_f32 v10, v168, v6, v228
	v_fma_f32 v11, v168, v7, v244
	v_fma_f32 v8, -v152, v5, v8
	v_fma_f32 v9, v152, v4, v9
	v_fma_f32 v10, -v154, v7, v10
	v_fma_f32 v11, v154, v6, v11
	v_fma_f32 v4, v166, v8, v97
	v_fma_f32 v5, v166, v9, v113
	v_fma_f32 v6, v168, v10, v229
	v_fma_f32 v7, v168, v11, v245
	v_fma_f32 v4, -v152, v9, v4
	v_fma_f32 v5, v152, v8, v5
	v_fma_f32 v6, -v154, v11, v6
	v_fma_f32 v7, v154, v10, v7
	v_fma_f32 v8, v166, v4, v98
	v_fma_f32 v9, v166, v5, v114
	v_fma_f32 v10, v168, v6, v230
	v_fma_f32 v11, v168, v7, v246
	v_fma_f32 v8, -v152, v5, v8
	v_fma_f32 v9, v152, v4, v9
	v_fma_f32 v10, -v154, v7, v10
	v_fma_f32 v11, v154, v6, v11
	v_fma_f32 v4, v166, v8, v99
	v_fma_f32 v5, v166, v9, v115
	v_fma_f32 v6, v168, v10, v231
	v_fma_f32 v7, v168, v11, v247
	v_fma_f32 v4, -v152, v9, v4
	v_fma_f32 v5, v152, v8, v5
	v_fma_f32 v6, -v154, v11, v6
	v_fma_f32 v7, v154, v10, v7
	global_store_dwordx2 v[12:13], v[4:5], off
	global_store_dwordx2 v[12:13], v[6:7], off offset:256
	s_andn2_b64 exec, exec, s[8:9]
	s_cbranch_execnz .LBB0_137
